# diff-attention matrix segment: LDS fragment reads run 6 ahead of the MFMAs instead of 4
# speedup vs baseline: 1.0548x; 1.0026x over previous
;     ...
;     for (int mp = 0; mp < 2; ++mp) {
;         const size_t hoff = ((size_t)(b * 8 + hh * 2 + mp) * 4096) * 64;
;         const bf16_t* Qb = (const bf16_t*)(p.ws + OFF_QD) + hoff;
;         const bf16_t* Kb = (const bf16_t*)(p.ws + OFF_KD) + hoff;
;         bf16x8 qf[4];
; #pragma unroll
;         for (int s = 0; s < 4; ++s) qf[s] = *(const bf16x8*)(Qb + (size_t)qpos * 64 + s * 16 + h * 8);
; #pragma unroll
;         for (int s = 0; s < 4; ++s) asm volatile("" : "+v"(qf[s]));
;         f32x16 o[4];
; #pragma unroll
;         for (int dt = 0; dt < 4; ++dt)
; #pragma unroll
;             for (int i = 0; i < 16; ++i) o[dt][i] = 0.f;
;         float m = -1e30f; f32x16 lv;
; #pragma unroll
;         for (int i = 0; i < 16; ++i) lv[i] = 0.f;
;         kv_loop<128, true>(lds, Kb, VTb, 4096, ntl, 0, [](int j) { return j + 1; }, [&](int j, const unsigned char* sb) {
;             const int k0 = j * 64;
.LBB0_467:
	v_or_b32_e32 v2, s4, v189
	v_lshlrev_b64 v[4:5], 1, v[2:3]
	v_lshl_add_u64 v[6:7], v[174:175], 0, v[4:5]
	global_load_dwordx4 v[130:133], v[6:7], off
	global_load_dwordx4 v[134:137], v[6:7], off offset:32
	global_load_dwordx4 v[138:141], v[6:7], off offset:64
	global_load_dwordx4 v[142:145], v[6:7], off offset:96
	v_lshl_add_u64 v[100:101], s[10:11], 0, v[4:5]
	v_mov_b32_e32 v173, v3
	v_lshl_add_u64 v[4:5], v[100:101], 0, v[170:171]
	v_lshl_add_u64 v[4:5], v[4:5], 0, v[172:173]
	v_mov_b32_e32 v16, v3
	v_mov_b32_e32 v17, v3
	v_mov_b32_e32 v6, v3
	v_mov_b32_e32 v7, v3
	v_mov_b32_e32 v8, v3
	v_mov_b32_e32 v9, v3
	v_mov_b32_e32 v10, v3
	v_mov_b32_e32 v11, v3
	v_mov_b32_e32 v12, v3
	v_mov_b32_e32 v13, v3
	v_mov_b32_e32 v14, v3
	v_mov_b32_e32 v15, v3
	v_mov_b32_e32 v2, v3
	s_xor_b64 s[20:21], s[2:3], -1
	v_mov_b32_e32 v98, 0
	v_mov_b32_e32 v163, 0xf149f2ca
	s_mov_b64 s[2:3], 0
	s_mov_b32 s24, 0
	s_waitcnt vmcnt(3)
	s_waitcnt vmcnt(2)
	s_waitcnt vmcnt(1)
	s_waitcnt vmcnt(0)
	global_load_dwordx4 v[146:149], v[4:5], off
	global_load_dwordx4 v[150:153], v[164:165], off
	global_load_dwordx4 v[154:157], v[166:167], off
	v_mov_b32_e32 v4, v3
	v_mov_b32_e32 v5, v3
	v_mov_b64_e32 v[32:33], v[16:17]
	v_mov_b64_e32 v[48:49], v[16:17]
	v_mov_b64_e32 v[64:65], v[16:17]
	v_mov_b64_e32 v[80:81], v[16:17]
	v_mov_b64_e32 v[96:97], v[16:17]
	v_mov_b64_e32 v[30:31], v[14:15]
	v_mov_b64_e32 v[28:29], v[12:13]
	v_mov_b64_e32 v[26:27], v[10:11]
	v_mov_b64_e32 v[24:25], v[8:9]
	v_mov_b64_e32 v[22:23], v[6:7]
	v_mov_b64_e32 v[20:21], v[4:5]
	v_mov_b64_e32 v[18:19], v[2:3]
	v_mov_b64_e32 v[46:47], v[14:15]
	v_mov_b64_e32 v[44:45], v[12:13]
	v_mov_b64_e32 v[42:43], v[10:11]
	v_mov_b64_e32 v[40:41], v[8:9]
	v_mov_b64_e32 v[38:39], v[6:7]
	v_mov_b64_e32 v[36:37], v[4:5]
	v_mov_b64_e32 v[34:35], v[2:3]
	v_mov_b64_e32 v[62:63], v[14:15]
	v_mov_b64_e32 v[60:61], v[12:13]
	v_mov_b64_e32 v[58:59], v[10:11]
	v_mov_b64_e32 v[56:57], v[8:9]
	v_mov_b64_e32 v[54:55], v[6:7]
	v_mov_b64_e32 v[52:53], v[4:5]
	v_mov_b64_e32 v[50:51], v[2:3]
	v_mov_b64_e32 v[78:79], v[14:15]
	v_mov_b64_e32 v[76:77], v[12:13]
	v_mov_b64_e32 v[74:75], v[10:11]
	v_mov_b64_e32 v[72:73], v[8:9]
	v_mov_b64_e32 v[70:71], v[6:7]
	v_mov_b64_e32 v[68:69], v[4:5]
	v_mov_b64_e32 v[66:67], v[2:3]
	v_mov_b64_e32 v[94:95], v[14:15]
	v_mov_b64_e32 v[92:93], v[12:13]
	v_mov_b64_e32 v[90:91], v[10:11]
	v_mov_b64_e32 v[88:89], v[8:9]
	v_mov_b64_e32 v[86:87], v[6:7]
	v_mov_b64_e32 v[84:85], v[4:5]
	v_mov_b64_e32 v[82:83], v[2:3]
	v_lshl_add_u64 v[4:5], v[100:101], 0, v[172:173]
	s_waitcnt vmcnt(2)
	ds_write_b128 v198, v[146:149]
	s_waitcnt vmcnt(1)
	ds_write2_b64 v182, v[150:151], v[152:153] offset0:128 offset1:130
	s_waitcnt vmcnt(0)
	ds_write2_b64 v183, v[154:155], v[156:157] offset0:128 offset1:130
	s_waitcnt lgkmcnt(0)
	s_barrier
	v_readfirstlane_b32 s58, v188
	v_readfirstlane_b32 s59, v186
	s_mov_b32 s24, 1

; template <int DV, bool HAS_V>
; DI void kv_gload(KVStage<DV>& st, const bf16_t* __restrict__ Kb, const bf16_t* __restrict__ VTb, int ldv, int key0) {
;     const int tid = threadIdx.x;
;     st.k[0] = *(const u32x4*)(Kb + (size_t)(key0 + (tid >> 3)) * 64 + (tid & 7) * 8);
;     if (HAS_V) {
; #pragma unroll
;         for (int i = 0; i < DV / 64; ++i) { const int c = tid + 512 * i; st.v[i] = *(const u32x4*)(VTb + (size_t)(key0 >> 6) * (DV * 64) + c * 8); }
;     }
; }
	s_lshl_b32 s66, s24, 6
	v_add_u32_e32 v8, s66, v187
	v_mov_b32_e32 v9, v3
	v_lshlrev_b64 v[8:9], 7, v[8:9]
	v_lshl_add_u64 v[8:9], v[4:5], 0, v[8:9]
	global_load_dwordx4 v[146:149], v[8:9], off
	s_lshl_b32 s66, s24, 14
	s_mov_b32 s67, 0
	v_lshl_add_u64 v[10:11], v[164:165], 0, s[66:67]
	global_load_dwordx4 v[150:153], v[10:11], off
	s_add_u32 s66, s66, 0x2000
	v_lshl_add_u64 v[10:11], v[164:165], 0, s[66:67]
	global_load_dwordx4 v[154:157], v[10:11], off

;     ...
;         kv_loop<128, true>(lds, Kb, VTb, 4096, ntl, 0, [](int j) { return j + 1; }, [&](int j, const unsigned char* sb) {
;             const int k0 = j * 64;
;             if (k0 <= wq0 + 31) {
	s_add_i32 s60, s59, 31
	s_mov_b32 s61, 0
	s_movk_i32 s62, 0x6c00
	s_mov_b32 s63, 0xd800
	v_add3_u32 v7, s61, v191, v168

; #define MFMA(a, b, c) __builtin_amdgcn_mfma_f32_32x32x16_bf16((a), (b), (c), 0, 0, 0)
; template <int DV, bool HAS_V>
; DI void kv_sstore(const KVStage<DV>& st, unsigned char* buf) {
;     const int tid = threadIdx.x;
;     *(u32x4*)(buf + (tid >> 3) * KP + (tid & 7) * 16) = st.k[0];
;     if (HAS_V) {
; #pragma unroll
;         for (int i = 0; i < DV / 64; ++i) {
;             const int c = tid + 512 * i, kc = c & 7; unsigned char* q = buf + KT_BYTES + (c >> 3) * VP + (kc >> 1) * 32 + (kc & 1) * 8;
;             u32x2 lo, hi; lo.x = st.v[i].x; lo.y = st.v[i].y; hi.x = st.v[i].z; hi.y = st.v[i].w;
;             *(u32x2*)q = lo; *(u32x2*)(q + 16) = hi;
;         }
;     }
; }
; DI void attn_scores(const unsigned char* kb, const bf16x8 (&qf)[4], int r, int h, f32x16& s0, f32x16& s1) {
; #pragma unroll
;     for (int i = 0; i < 16; ++i) { s0[i] = 0.f; s1[i] = 0.f; }
; #pragma unroll
;     for (int s = 0; s < 4; ++s) {
;         const bf16x8 k0 = *(const bf16x8*)(kb + r * KP + s * 32 + h * 16);
;         const bf16x8 k1 = *(const bf16x8*)(kb + (32 + r) * KP + s * 32 + h * 16);
;         s0 = MFMA(k0, qf[s], s0); s1 = MFMA(k1, qf[s], s1);
;     }
; }
	ds_read_b128 v[214:217], v7 offset:0
	ds_read_b128 v[218:221], v7 offset:4608
	ds_read_b128 v[222:225], v7 offset:32
	ds_read_b128 v[226:229], v7 offset:4640
	ds_read_b128 v[230:233], v7 offset:64
	ds_read_b128 v[234:237], v7 offset:4672
	s_waitcnt lgkmcnt(5)
	v_mfma_f32_32x32x16_bf16 v[114:129], v[214:217], v[130:133], 0
	ds_read_b128 v[214:217], v7 offset:96
	s_waitcnt lgkmcnt(5)
	v_mfma_f32_32x32x16_bf16 v[98:113], v[218:221], v[130:133], 0
	ds_read_b128 v[218:221], v7 offset:4704
	s_waitcnt lgkmcnt(5)
	v_mfma_f32_32x32x16_bf16 v[114:129], v[222:225], v[134:137], v[114:129]
	s_waitcnt lgkmcnt(4)
	v_mfma_f32_32x32x16_bf16 v[98:113], v[226:229], v[134:137], v[98:113]
	s_waitcnt lgkmcnt(3)
	v_mfma_f32_32x32x16_bf16 v[114:129], v[230:233], v[138:141], v[114:129]
	s_waitcnt lgkmcnt(2)
	v_mfma_f32_32x32x16_bf16 v[98:113], v[234:237], v[138:141], v[98:113]
	s_waitcnt lgkmcnt(1)
	v_mfma_f32_32x32x16_bf16 v[114:129], v[214:217], v[142:145], v[114:129]
	s_waitcnt lgkmcnt(0)
	v_mfma_f32_32x32x16_bf16 v[98:113], v[218:221], v[142:145], v[98:113]
	s_waitcnt vmcnt(0)
	v_add3_u32 v2, s62, v159, v195
	ds_write_b128 v2, v[146:149]
	v_add3_u32 v2, s62, v196, v197
	v_add_u32_e32 v7, v2, v159
	v_add_u32_e32 v2, v2, v180
	v_add_u32_e32 v7, 0x2000, v7
	v_add_u32_e32 v2, 0x2000, v2
	ds_write2_b64 v7, v[150:151], v[152:153] offset0:128 offset1:130
	ds_write2_b64 v2, v[154:155], v[156:157] offset0:128 offset1:130

;     ...
;     for (int i = 0; i < nt; ++i) {
;         const int j = jn;
;         const bool more = (i + 1 < nt);
;         if (more) { jn = next(j); if (probe != 1) kv_gload<DV, HAS_V>(st, Kb, VTb, ldv, jn * 64); }
	s_mov_b32 s24, 2
	s_waitcnt lgkmcnt(0)

; template <int DV, bool HAS_V>
; DI void kv_gload(KVStage<DV>& st, const bf16_t* __restrict__ Kb, const bf16_t* __restrict__ VTb, int ldv, int key0) {
;     const int tid = threadIdx.x;
;     st.k[0] = *(const u32x4*)(Kb + (size_t)(key0 + (tid >> 3)) * 64 + (tid & 7) * 8);
;     if (HAS_V) {
; #pragma unroll
;         for (int i = 0; i < DV / 64; ++i) { const int c = tid + 512 * i; st.v[i] = *(const u32x4*)(VTb + (size_t)(key0 >> 6) * (DV * 64) + c * 8); }
;     }
; }
	s_lshl_b32 s66, s24, 6
	v_add_u32_e32 v8, s66, v187
	v_mov_b32_e32 v9, v3
	v_lshlrev_b64 v[8:9], 7, v[8:9]
	v_lshl_add_u64 v[8:9], v[4:5], 0, v[8:9]
	global_load_dwordx4 v[146:149], v[8:9], off
	s_lshl_b32 s66, s24, 14
	s_mov_b32 s67, 0
	v_lshl_add_u64 v[10:11], v[164:165], 0, s[66:67]
	global_load_dwordx4 v[150:153], v[10:11], off
	s_add_u32 s66, s66, 0x2000
	v_lshl_add_u64 v[10:11], v[164:165], 0, s[66:67]
	global_load_dwordx4 v[154:157], v[10:11], off

;     constexpr int SB = KT_BYTES + (HAS_V ? DV * VP : 0);
;     KVStage<DV> st;
;     int jn = j0;
;     if (probe != 1) { kv_gload<DV, HAS_V>(st, Kb, VTb, ldv, jn * 64); kv_sstore<DV, HAS_V>(st, lds); }
;     __syncthreads();
;     for (int i = 0; i < nt; ++i) {
	s_mov_b32 s24, 0
	s_cmp_eq_u32 s54, 0
	s_cbranch_scc1 .Ldl_loop
	s_barrier

;     ...
;     for (int i = 0; i < nt; ++i) {
;         const int j = jn;
;         const bool more = (i + 1 < nt);
;         if (more) { jn = next(j); if (probe != 1) kv_gload<DV, HAS_V>(st, Kb, VTb, ldv, jn * 64); }
;         if (probe != 2) body(j, (const unsigned char*)(lds + (i & 1) * SB));
.Ldl_xdone:
	s_waitcnt lgkmcnt(0)
	s_barrier
	s_setprio 3
	s_cmp_le_i32 s64, s60
	s_cbranch_scc0 .Ldl_stage
	v_add3_u32 v199, s61, v168, v191
	s_add_i32 s65, s24, 1
	s_cmp_ge_u32 s65, s58
	s_cbranch_scc1 .Ldl_pvonly
	s_lshl_b32 s66, s65, 6
	s_cmp_le_i32 s66, s60
	s_cbranch_scc0 .Ldl_pvonly
	v_add3_u32 v7, s62, v191, v168

; #define MFMA(a, b, c) __builtin_amdgcn_mfma_f32_32x32x16_bf16((a), (b), (c), 0, 0, 0)
; DI void attn_scores(const unsigned char* kb, const bf16x8 (&qf)[4], int r, int h, f32x16& s0, f32x16& s1) {
; #pragma unroll
;     for (int i = 0; i < 16; ++i) { s0[i] = 0.f; s1[i] = 0.f; }
; #pragma unroll
;     for (int s = 0; s < 4; ++s) {
;         const bf16x8 k0 = *(const bf16x8*)(kb + r * KP + s * 32 + h * 16);
;         const bf16x8 k1 = *(const bf16x8*)(kb + (32 + r) * KP + s * 32 + h * 16);
;         s0 = MFMA(k0, qf[s], s0); s1 = MFMA(k1, qf[s], s1);
;     }
; }
; template <int DV>
; DI void attn_pv(const unsigned char* vb, const bf16x8 (&pf)[2][2], int r, int h, f32x16 (&o)[DV / 32]) {
; #pragma unroll
;     for (int dt = 0; dt < DV / 32; ++dt)
; #pragma unroll
;         for (int mt = 0; mt < 2; ++mt)
; #pragma unroll
;             for (int sp = 0; sp < 2; ++sp) {
;                 const bf16x8 vf = *(const bf16x8*)(vb + (dt * 32 + r) * VP + (2 * mt + sp) * 32 + h * 16);
;                 o[dt] = MFMA(vf, pf[mt][sp], o[dt]);
;             }
; }
	ds_read_b128 v[214:217], v199 offset:9216
	ds_read_b128 v[218:221], v199 offset:9248
	ds_read_b128 v[222:225], v199 offset:9280
	ds_read_b128 v[226:229], v199 offset:9312
	ds_read_b128 v[230:233], v199 offset:13824
	ds_read_b128 v[234:237], v199 offset:13856
	s_waitcnt lgkmcnt(5)
	v_mfma_f32_32x32x16_bf16 v[66:81], v[214:217], v[200:203], v[66:81]
	ds_read_b128 v[214:217], v199 offset:13888
	s_waitcnt lgkmcnt(5)
	v_mfma_f32_32x32x16_bf16 v[66:81], v[218:221], v[204:207], v[66:81]
	ds_read_b128 v[218:221], v199 offset:13920
	s_waitcnt lgkmcnt(5)
	v_mfma_f32_32x32x16_bf16 v[66:81], v[222:225], v[208:211], v[66:81]
	ds_read_b128 v[222:225], v199 offset:18432
	s_waitcnt lgkmcnt(5)
	v_mfma_f32_32x32x16_bf16 v[66:81], v[226:229], v[12:15], v[66:81]
	ds_read_b128 v[226:229], v199 offset:18464
	s_waitcnt lgkmcnt(5)
	v_mfma_f32_32x32x16_bf16 v[50:65], v[230:233], v[200:203], v[50:65]
	ds_read_b128 v[230:233], v199 offset:18496
	s_waitcnt lgkmcnt(5)
	v_mfma_f32_32x32x16_bf16 v[50:65], v[234:237], v[204:207], v[50:65]
	ds_read_b128 v[234:237], v199 offset:18528
	s_waitcnt lgkmcnt(5)
	v_mfma_f32_32x32x16_bf16 v[50:65], v[214:217], v[208:211], v[50:65]
	ds_read_b128 v[214:217], v199 offset:23040
	s_waitcnt lgkmcnt(5)
	v_mfma_f32_32x32x16_bf16 v[50:65], v[218:221], v[12:15], v[50:65]
	ds_read_b128 v[218:221], v199 offset:23072
	s_waitcnt lgkmcnt(5)
	v_mfma_f32_32x32x16_bf16 v[34:49], v[222:225], v[200:203], v[34:49]
	ds_read_b128 v[222:225], v199 offset:23104
	s_waitcnt lgkmcnt(5)
	v_mfma_f32_32x32x16_bf16 v[34:49], v[226:229], v[204:207], v[34:49]
	ds_read_b128 v[226:229], v199 offset:23136
	s_waitcnt lgkmcnt(5)
	v_mfma_f32_32x32x16_bf16 v[34:49], v[230:233], v[208:211], v[34:49]
	ds_read_b128 v[230:233], v7 offset:0
	s_waitcnt lgkmcnt(5)
	v_mfma_f32_32x32x16_bf16 v[34:49], v[234:237], v[12:15], v[34:49]
	ds_read_b128 v[234:237], v7 offset:4608
	s_waitcnt lgkmcnt(5)
	v_mfma_f32_32x32x16_bf16 v[18:33], v[214:217], v[200:203], v[18:33]
	ds_read_b128 v[214:217], v7 offset:32
	s_waitcnt lgkmcnt(5)
	v_mfma_f32_32x32x16_bf16 v[18:33], v[218:221], v[204:207], v[18:33]
	ds_read_b128 v[218:221], v7 offset:4640
	s_waitcnt lgkmcnt(5)
	v_mfma_f32_32x32x16_bf16 v[18:33], v[222:225], v[208:211], v[18:33]
	ds_read_b128 v[222:225], v7 offset:64
	s_waitcnt lgkmcnt(5)
	v_mfma_f32_32x32x16_bf16 v[18:33], v[226:229], v[12:15], v[18:33]
	ds_read_b128 v[226:229], v7 offset:4672
	s_waitcnt lgkmcnt(5)
	v_mfma_f32_32x32x16_bf16 v[114:129], v[230:233], v[130:133], 0
	ds_read_b128 v[230:233], v7 offset:96
	s_waitcnt lgkmcnt(5)
	v_mfma_f32_32x32x16_bf16 v[98:113], v[234:237], v[130:133], 0
	ds_read_b128 v[234:237], v7 offset:4704
	s_waitcnt lgkmcnt(5)
	v_mfma_f32_32x32x16_bf16 v[114:129], v[214:217], v[134:137], v[114:129]
	s_waitcnt lgkmcnt(4)
	v_mfma_f32_32x32x16_bf16 v[98:113], v[218:221], v[134:137], v[98:113]
	s_waitcnt lgkmcnt(3)
	v_mfma_f32_32x32x16_bf16 v[114:129], v[222:225], v[138:141], v[114:129]
	s_waitcnt lgkmcnt(2)
	v_mfma_f32_32x32x16_bf16 v[98:113], v[226:229], v[138:141], v[98:113]
	s_waitcnt lgkmcnt(1)
	v_mfma_f32_32x32x16_bf16 v[114:129], v[230:233], v[142:145], v[114:129]
	s_waitcnt lgkmcnt(0)
	v_mfma_f32_32x32x16_bf16 v[98:113], v[234:237], v[142:145], v[98:113]
	s_branch .Ldl_stage
.Ldl_pvonly:
	ds_read_b128 v[214:217], v199 offset:9216
	ds_read_b128 v[218:221], v199 offset:9248
	ds_read_b128 v[222:225], v199 offset:9280
	ds_read_b128 v[226:229], v199 offset:9312
	ds_read_b128 v[230:233], v199 offset:13824
	ds_read_b128 v[234:237], v199 offset:13856
	s_waitcnt lgkmcnt(5)
	v_mfma_f32_32x32x16_bf16 v[66:81], v[214:217], v[200:203], v[66:81]
	ds_read_b128 v[214:217], v199 offset:13888
	s_waitcnt lgkmcnt(5)
	v_mfma_f32_32x32x16_bf16 v[66:81], v[218:221], v[204:207], v[66:81]
	ds_read_b128 v[218:221], v199 offset:13920
	s_waitcnt lgkmcnt(5)
	v_mfma_f32_32x32x16_bf16 v[66:81], v[222:225], v[208:211], v[66:81]
	ds_read_b128 v[222:225], v199 offset:18432
	s_waitcnt lgkmcnt(5)
	v_mfma_f32_32x32x16_bf16 v[66:81], v[226:229], v[12:15], v[66:81]
	ds_read_b128 v[226:229], v199 offset:18464
	s_waitcnt lgkmcnt(5)
	v_mfma_f32_32x32x16_bf16 v[50:65], v[230:233], v[200:203], v[50:65]
	ds_read_b128 v[230:233], v199 offset:18496
	s_waitcnt lgkmcnt(5)
	v_mfma_f32_32x32x16_bf16 v[50:65], v[234:237], v[204:207], v[50:65]
	ds_read_b128 v[234:237], v199 offset:18528
	s_waitcnt lgkmcnt(5)
	v_mfma_f32_32x32x16_bf16 v[50:65], v[214:217], v[208:211], v[50:65]
	ds_read_b128 v[214:217], v199 offset:23040
	s_waitcnt lgkmcnt(5)
	v_mfma_f32_32x32x16_bf16 v[50:65], v[218:221], v[12:15], v[50:65]
	ds_read_b128 v[218:221], v199 offset:23072
	s_waitcnt lgkmcnt(5)
	v_mfma_f32_32x32x16_bf16 v[34:49], v[222:225], v[200:203], v[34:49]
	ds_read_b128 v[222:225], v199 offset:23104
	s_waitcnt lgkmcnt(5)
	v_mfma_f32_32x32x16_bf16 v[34:49], v[226:229], v[204:207], v[34:49]
	ds_read_b128 v[226:229], v199 offset:23136
	s_waitcnt lgkmcnt(5)
	v_mfma_f32_32x32x16_bf16 v[34:49], v[230:233], v[208:211], v[34:49]
	s_waitcnt lgkmcnt(4)
	v_mfma_f32_32x32x16_bf16 v[34:49], v[234:237], v[12:15], v[34:49]
	s_waitcnt lgkmcnt(3)
	v_mfma_f32_32x32x16_bf16 v[18:33], v[214:217], v[200:203], v[18:33]
	s_waitcnt lgkmcnt(2)
	v_mfma_f32_32x32x16_bf16 v[18:33], v[218:221], v[204:207], v[18:33]
	s_waitcnt lgkmcnt(1)
	v_mfma_f32_32x32x16_bf16 v[18:33], v[222:225], v[208:211], v[18:33]
	s_waitcnt lgkmcnt(0)
	v_mfma_f32_32x32x16_bf16 v[18:33], v[226:229], v[12:15], v[18:33]
